# v13: v12 + indexer scoring: waves 4-7 score the previous chunk before issuing the current chunk's MFMAs (half-iteration stagger between SIMD partners)
# baseline (speedup 1.0000x reference)
.Lidx_pro1:
	v_readlane_b32 s1, v253, 23
	s_nop 3
	s_lshr_b32 s1, s1, 2
	s_barrier
	s_cmp_lg_u32 s1, 0
	s_cbranch_scc1 .Lidx_lag_loop

.Lidx_lag_loop:
	v_add_u32_e32 v76, s11, v73
	ds_read_b128 v[118:121], v76
	ds_read_b128 v[126:129], v76 offset:4608
	ds_read_b128 v[114:117], v76 offset:32
	ds_read_b128 v[122:125], v76 offset:4640
	ds_read_b128 v[110:113], v76 offset:64
	ds_read_b128 v[106:109], v76 offset:4672
	ds_read_b128 v[86:89], v76 offset:4704
	ds_read_b128 v[102:105], v76 offset:96
	s_cmp_eq_u32 s2, 0
	s_cbranch_scc1 .Lidx_lag_novalu
	v_max_i32_e32 v2, 0, v2
	v_fma_f32 v2, v50, v2, 0
	v_max_i32_e32 v10, 0, v10
	v_max_i32_e32 v3, 0, v3
	v_fma_f32 v10, v58, v10, 0
	v_fmac_f32_e32 v2, v51, v3
	v_max_i32_e32 v3, 0, v11
	v_max_i32_e32 v18, 0, v18
	v_fma_f32 v18, v50, v18, 0
	v_max_i32_e32 v26, 0, v26
	v_max_i32_e32 v19, 0, v19
	v_fma_f32 v26, v58, v26, 0
	v_fmac_f32_e32 v18, v51, v19
	v_max_i32_e32 v19, 0, v27
	v_fmac_f32_e32 v10, v59, v3
	v_max_i32_e32 v3, 0, v20
	v_fmac_f32_e32 v26, v59, v19
	v_fmac_f32_e32 v18, v52, v3
	v_max_i32_e32 v3, 0, v28
	v_fmac_f32_e32 v26, v60, v3
	v_max_i32_e32 v3, 0, v4
	v_fmac_f32_e32 v2, v52, v3
	v_max_i32_e32 v3, 0, v12
	v_fmac_f32_e32 v10, v60, v3
	v_max_i32_e32 v3, 0, v21
	v_fmac_f32_e32 v18, v53, v3
	v_max_i32_e32 v3, 0, v29
	v_fmac_f32_e32 v26, v61, v3
	v_max_i32_e32 v3, 0, v5
	v_fmac_f32_e32 v2, v53, v3
	v_max_i32_e32 v3, 0, v13
	v_fmac_f32_e32 v10, v61, v3
	v_max_i32_e32 v3, 0, v22
	v_fmac_f32_e32 v18, v54, v3
	v_max_i32_e32 v3, 0, v30
	v_fmac_f32_e32 v26, v62, v3
	v_max_i32_e32 v3, 0, v6
	v_fmac_f32_e32 v2, v54, v3
	v_max_i32_e32 v3, 0, v14
	v_fmac_f32_e32 v10, v62, v3
	v_max_i32_e32 v3, 0, v23
	v_fmac_f32_e32 v18, v55, v3
	v_max_i32_e32 v3, 0, v31
	v_fmac_f32_e32 v26, v63, v3
	v_max_i32_e32 v3, 0, v7
	v_fmac_f32_e32 v2, v55, v3
	v_max_i32_e32 v3, 0, v15
	v_fmac_f32_e32 v10, v63, v3
	v_max_i32_e32 v3, 0, v24
	v_fmac_f32_e32 v18, v56, v3
	v_max_i32_e32 v3, 0, v32
	v_fmac_f32_e32 v26, v64, v3
	v_max_i32_e32 v3, 0, v8
	v_fmac_f32_e32 v2, v56, v3
	v_max_i32_e32 v3, 0, v16
	v_fmac_f32_e32 v10, v64, v3
	v_max_i32_e32 v3, 0, v25
	v_fmac_f32_e32 v18, v57, v3
	v_max_i32_e32 v3, 0, v33
	v_fmac_f32_e32 v26, v65, v3
	v_max_i32_e32 v3, 0, v9
	v_fmac_f32_e32 v2, v57, v3
	v_max_i32_e32 v3, 0, v17
	v_fmac_f32_e32 v10, v65, v3
	v_mov_b32_e32 v3, v18
	v_mov_b32_e32 v5, v26
	v_mov_b32_e32 v4, v2
	v_mov_b32_e32 v6, v10
	v_permlane32_swap_b32_e32 v18, v3
	v_permlane32_swap_b32_e32 v26, v5
	v_permlane32_swap_b32_e32 v2, v4
	v_permlane32_swap_b32_e32 v10, v6
	s_and_saveexec_b64 s[6:7], s[4:5]
	s_xor_b64 s[6:7], exec, s[6:7]
	v_add_f32_e32 v2, v10, v6
	v_add_f32_e32 v3, v26, v5
	ds_write2_b32 v0, v3, v2 offset1:32
	s_andn2_saveexec_b64 s[6:7], s[6:7]
	v_add_f32_e32 v2, v2, v4
	v_add_f32_e32 v3, v18, v3
	ds_write2_b32 v251, v3, v2 offset1:32
	s_or_b64 exec, exec, s[6:7]
	v_add_u32_e32 v0, 0x100, v0
	v_add_u32_e32 v251, 0x100, v251
.Lidx_lag_novalu:
	s_waitcnt lgkmcnt(0)
	v_mfma_f32_32x32x16_bf16 v[18:33], v[34:37], v[118:121], 0
	v_mfma_f32_32x32x16_bf16 v[2:17], v[34:37], v[126:129], 0
	v_mfma_f32_32x32x16_bf16 v[18:33], v[38:41], v[114:117], v[18:33]
	v_mfma_f32_32x32x16_bf16 v[2:17], v[38:41], v[122:125], v[2:17]
	v_mfma_f32_32x32x16_bf16 v[18:33], v[42:45], v[110:113], v[18:33]
	v_mfma_f32_32x32x16_bf16 v[2:17], v[42:45], v[106:109], v[2:17]
	v_mfma_f32_32x32x16_bf16 v[2:17], v[46:49], v[86:89], v[2:17]
	v_mfma_f32_32x32x16_bf16 v[18:33], v[46:49], v[102:105], v[18:33]
	s_add_i32 s2, s2, 1
	s_cmp_ge_u32 s2, s8
	s_cbranch_scc1 .Lidx_lag_done
	s_xor_b32 s11, s11, 0x2400
	s_waitcnt vmcnt(0)
	v_add_u32_e32 v76, s11, v72
	ds_write_b128 v76, v[66:69]
	s_waitcnt lgkmcnt(0)
	s_add_i32 s0, s2, 1
	s_cmp_ge_u32 s0, s8
	s_cbranch_scc1 .Lidx_lag_nold
	global_load_dwordx4 v[66:69], v[70:71], off
	v_lshl_add_u64 v[70:71], v[70:71], 0, s[12:13]

.Lidx_lag_done:
	s_nop 10
	v_max_i32_e32 v2, 0, v2
	v_fma_f32 v2, v50, v2, 0
	v_max_i32_e32 v10, 0, v10
	v_max_i32_e32 v3, 0, v3
	v_fma_f32 v10, v58, v10, 0
	v_fmac_f32_e32 v2, v51, v3
	v_max_i32_e32 v3, 0, v11
	v_max_i32_e32 v18, 0, v18
	v_fma_f32 v18, v50, v18, 0
	v_max_i32_e32 v26, 0, v26
	v_max_i32_e32 v19, 0, v19
	v_fma_f32 v26, v58, v26, 0
	v_fmac_f32_e32 v18, v51, v19
	v_max_i32_e32 v19, 0, v27
	v_fmac_f32_e32 v10, v59, v3
	v_max_i32_e32 v3, 0, v20
	v_fmac_f32_e32 v26, v59, v19
	v_fmac_f32_e32 v18, v52, v3
	v_max_i32_e32 v3, 0, v28
	v_fmac_f32_e32 v26, v60, v3
	v_max_i32_e32 v3, 0, v4
	v_fmac_f32_e32 v2, v52, v3
	v_max_i32_e32 v3, 0, v12
	v_fmac_f32_e32 v10, v60, v3
	v_max_i32_e32 v3, 0, v21
	v_fmac_f32_e32 v18, v53, v3
	v_max_i32_e32 v3, 0, v29
	v_fmac_f32_e32 v26, v61, v3
	v_max_i32_e32 v3, 0, v5
	v_fmac_f32_e32 v2, v53, v3
	v_max_i32_e32 v3, 0, v13
	v_fmac_f32_e32 v10, v61, v3
	v_max_i32_e32 v3, 0, v22
	v_fmac_f32_e32 v18, v54, v3
	v_max_i32_e32 v3, 0, v30
	v_fmac_f32_e32 v26, v62, v3
	v_max_i32_e32 v3, 0, v6
	v_fmac_f32_e32 v2, v54, v3
	v_max_i32_e32 v3, 0, v14
	v_fmac_f32_e32 v10, v62, v3
	v_max_i32_e32 v3, 0, v23
	v_fmac_f32_e32 v18, v55, v3
	v_max_i32_e32 v3, 0, v31
	v_fmac_f32_e32 v26, v63, v3
	v_max_i32_e32 v3, 0, v7
	v_fmac_f32_e32 v2, v55, v3
	v_max_i32_e32 v3, 0, v15
	v_fmac_f32_e32 v10, v63, v3
	v_max_i32_e32 v3, 0, v24
	v_fmac_f32_e32 v18, v56, v3
	v_max_i32_e32 v3, 0, v32
	v_fmac_f32_e32 v26, v64, v3
	v_max_i32_e32 v3, 0, v8
	v_fmac_f32_e32 v2, v56, v3
	v_max_i32_e32 v3, 0, v16
	v_fmac_f32_e32 v10, v64, v3
	v_max_i32_e32 v3, 0, v25
	v_fmac_f32_e32 v18, v57, v3
	v_max_i32_e32 v3, 0, v33
	v_fmac_f32_e32 v26, v65, v3
	v_max_i32_e32 v3, 0, v9
	v_fmac_f32_e32 v2, v57, v3
	v_max_i32_e32 v3, 0, v17
	v_fmac_f32_e32 v10, v65, v3
	v_mov_b32_e32 v3, v18
	v_mov_b32_e32 v5, v26
	v_mov_b32_e32 v4, v2
	v_mov_b32_e32 v6, v10
	v_permlane32_swap_b32_e32 v18, v3
	v_permlane32_swap_b32_e32 v26, v5
	v_permlane32_swap_b32_e32 v2, v4
	v_permlane32_swap_b32_e32 v10, v6
	s_and_saveexec_b64 s[6:7], s[4:5]
	s_xor_b64 s[6:7], exec, s[6:7]
	v_add_f32_e32 v2, v10, v6
	v_add_f32_e32 v3, v26, v5
	ds_write2_b32 v0, v3, v2 offset1:32
	s_andn2_saveexec_b64 s[6:7], s[6:7]
	v_add_f32_e32 v2, v2, v4
	v_add_f32_e32 v3, v18, v3
	ds_write2_b32 v251, v3, v2 offset1:32
	s_or_b64 exec, exec, s[6:7]
	v_add_u32_e32 v0, 0x100, v0
	v_add_u32_e32 v251, 0x100, v251
